# attention K-loop pipelined LDS reads, XCD-local attention queues, compact bf16 GEMM epilogues, ff1 8x8 tile order, ff1 weight warm-up in norm phase
# speedup vs baseline: 1.0299x; 1.0188x over previous
; DI bf16_t f2bf(float x) { unsigned r; asm("v_cvt_pk_bf16_f32 %0, %1, %1" : "=v"(r) : "v"(x)); return (bf16_t)r; }
; DI int crow(int reg, int h) { return (reg & 3) + 8 * (reg >> 2) + 4 * h; }
; #define XCD_TILE_LOOP(MT, NTN, m_, n_) for (int lt_ = (bid >> 3), m_ = 0, n_ = 0; (lt_ < ((MT) >> 3) * (NTN)) && ((m_ = (bid & 7) + 8 * (lt_ / (NTN))), (n_ = lt_ % (NTN)), true); lt_ += (G >> 3))
; template <class Epi, class ColV>
; DI void gemm_tile(const bf16_t* __restrict__ A, int lda, const bf16_t* __restrict__ Bt, int ldb, int K, int m0, int n0, unsigned char* smem, Epi epi, ColV colv, const bf16_t* __restrict__ HYT = nullptr) {
;     ...
;     const float cv0 = colv(m0, n0 + 64 * wc + li), cv1 = colv(m0, n0 + 64 * wc + 32 + li);
; #pragma unroll
;     for (int mi = 0; mi < 2; ++mi)
; #pragma unroll
;         for (int ni = 0; ni < 2; ++ni)
; #pragma unroll
;             for (int reg = 0; reg < 16; ++reg)
;                 epi(m0 + 64 * wr + 32 * mi + crow(reg, lh), n0 + 64 * wc + 32 * ni + li, acc[mi][ni][reg], ni ? cv1 : cv0);
;     ...
;         bf16_t* HID = (bf16_t*)(p.ws + WS_HID);
;         auto epi = [&](int r, int c, float v, float) { const float a = fmaxf(v, 0.f); HID[(size_t)r * 4096 + c] = f2bf(a * a); };
;         auto nocol = [&](int, int) { return 0.f; };
;         XCD_TILE_LOOP((layer == 0 ? NT : NL) / 128, 32, tm, tn) gemm_tile((const bf16_t*)(p.ws + WS_H), 1024, (const bf16_t*)(p.ws + wbase(layer) + W_FF1), 1024, 1024, tm * 128, tn * 128, smem, epi, nocol);
.LBB0_53:
	v_add_u32_e32 v0, s39, v193
	v_lshl_or_b32 v0, v166, 2, v0
	v_or3_b32 v1, v151, s38, v148
	v_lshlrev_b32_e32 v0, 13, v0
	v_lshl_add_u32 v0, v1, 1, v0
	v_max_f32_e32 v1, 0, v52
	v_max_f32_e32 v2, 0, v36
	v_mul_f32_e32 v1, v1, v1
	v_mul_f32_e32 v2, v2, v2
	v_cvt_pk_bf16_f32 v1, v1, v1
	v_cvt_pk_bf16_f32 v2, v2, v2
	global_store_short v0, v1, s[2:3]
	global_store_short v0, v2, s[2:3] offset:64
	v_add_u32_e32 v0, 0x2000, v0
	v_max_f32_e32 v70, 0, v53
	v_max_f32_e32 v71, 0, v37
	v_mul_f32_e32 v70, v70, v70
	v_mul_f32_e32 v71, v71, v71
	v_cvt_pk_bf16_f32 v70, v70, v70
	v_cvt_pk_bf16_f32 v71, v71, v71
	global_store_short v0, v70, s[2:3]
	global_store_short v0, v71, s[2:3] offset:64
	v_add_u32_e32 v0, 0x2000, v0
	v_max_f32_e32 v1, 0, v54
	v_max_f32_e32 v2, 0, v38
	v_mul_f32_e32 v1, v1, v1
	v_mul_f32_e32 v2, v2, v2
	v_cvt_pk_bf16_f32 v1, v1, v1
	v_cvt_pk_bf16_f32 v2, v2, v2
	global_store_short v0, v1, s[2:3]
	global_store_short v0, v2, s[2:3] offset:64
	v_add_u32_e32 v0, 0x2000, v0
	v_max_f32_e32 v70, 0, v55
	v_max_f32_e32 v71, 0, v39
	v_mul_f32_e32 v70, v70, v70
	v_mul_f32_e32 v71, v71, v71
	v_cvt_pk_bf16_f32 v70, v70, v70
	v_cvt_pk_bf16_f32 v71, v71, v71
	global_store_short v0, v70, s[2:3]
	global_store_short v0, v71, s[2:3] offset:64
	v_add_u32_e32 v0, 0xa000, v0
	v_max_f32_e32 v1, 0, v56
	v_max_f32_e32 v2, 0, v40
	v_mul_f32_e32 v1, v1, v1
	v_mul_f32_e32 v2, v2, v2
	v_cvt_pk_bf16_f32 v1, v1, v1
	v_cvt_pk_bf16_f32 v2, v2, v2
	global_store_short v0, v1, s[2:3]
	global_store_short v0, v2, s[2:3] offset:64
	v_add_u32_e32 v0, 0x2000, v0
	v_max_f32_e32 v70, 0, v57
	v_max_f32_e32 v71, 0, v41
	v_mul_f32_e32 v70, v70, v70
	v_mul_f32_e32 v71, v71, v71
	v_cvt_pk_bf16_f32 v70, v70, v70
	v_cvt_pk_bf16_f32 v71, v71, v71
	global_store_short v0, v70, s[2:3]
	global_store_short v0, v71, s[2:3] offset:64
	v_add_u32_e32 v0, 0x2000, v0
	v_max_f32_e32 v1, 0, v58
	v_max_f32_e32 v2, 0, v42
	v_mul_f32_e32 v1, v1, v1
	v_mul_f32_e32 v2, v2, v2
	v_cvt_pk_bf16_f32 v1, v1, v1
	v_cvt_pk_bf16_f32 v2, v2, v2
	global_store_short v0, v1, s[2:3]
	global_store_short v0, v2, s[2:3] offset:64
	v_add_u32_e32 v0, 0x2000, v0
	v_max_f32_e32 v70, 0, v59
	v_max_f32_e32 v71, 0, v43
	v_mul_f32_e32 v70, v70, v70
	v_mul_f32_e32 v71, v71, v71
	v_cvt_pk_bf16_f32 v70, v70, v70
	v_cvt_pk_bf16_f32 v71, v71, v71
	global_store_short v0, v70, s[2:3]
	global_store_short v0, v71, s[2:3] offset:64
	v_add_u32_e32 v0, 0xa000, v0
	v_max_f32_e32 v1, 0, v60
	v_max_f32_e32 v2, 0, v44
	v_mul_f32_e32 v1, v1, v1
	v_mul_f32_e32 v2, v2, v2
	v_cvt_pk_bf16_f32 v1, v1, v1
	v_cvt_pk_bf16_f32 v2, v2, v2
	global_store_short v0, v1, s[2:3]
	global_store_short v0, v2, s[2:3] offset:64
	v_add_u32_e32 v0, 0x2000, v0
	v_max_f32_e32 v70, 0, v61
	v_max_f32_e32 v71, 0, v45
	v_mul_f32_e32 v70, v70, v70
	v_mul_f32_e32 v71, v71, v71
	v_cvt_pk_bf16_f32 v70, v70, v70
	v_cvt_pk_bf16_f32 v71, v71, v71
	global_store_short v0, v70, s[2:3]
	global_store_short v0, v71, s[2:3] offset:64
	v_add_u32_e32 v0, 0x2000, v0
	v_max_f32_e32 v1, 0, v62
	v_max_f32_e32 v2, 0, v46
	v_mul_f32_e32 v1, v1, v1
	v_mul_f32_e32 v2, v2, v2
	v_cvt_pk_bf16_f32 v1, v1, v1
	v_cvt_pk_bf16_f32 v2, v2, v2
	global_store_short v0, v1, s[2:3]
	global_store_short v0, v2, s[2:3] offset:64
	v_add_u32_e32 v0, 0x2000, v0
	v_max_f32_e32 v70, 0, v63
	v_max_f32_e32 v71, 0, v47
	v_mul_f32_e32 v70, v70, v70
	v_mul_f32_e32 v71, v71, v71
	v_cvt_pk_bf16_f32 v70, v70, v70
	v_cvt_pk_bf16_f32 v71, v71, v71
	global_store_short v0, v70, s[2:3]
	global_store_short v0, v71, s[2:3] offset:64
	v_add_u32_e32 v0, 0xa000, v0
	v_max_f32_e32 v1, 0, v64
	v_max_f32_e32 v2, 0, v48
	v_mul_f32_e32 v1, v1, v1
	v_mul_f32_e32 v2, v2, v2
	v_cvt_pk_bf16_f32 v1, v1, v1
	v_cvt_pk_bf16_f32 v2, v2, v2
	global_store_short v0, v1, s[2:3]
	global_store_short v0, v2, s[2:3] offset:64
	v_add_u32_e32 v0, 0x2000, v0
	v_max_f32_e32 v70, 0, v65
	v_max_f32_e32 v71, 0, v49
	v_mul_f32_e32 v70, v70, v70
	v_mul_f32_e32 v71, v71, v71
	v_cvt_pk_bf16_f32 v70, v70, v70
	v_cvt_pk_bf16_f32 v71, v71, v71
	global_store_short v0, v70, s[2:3]
	global_store_short v0, v71, s[2:3] offset:64
	v_add_u32_e32 v0, 0x2000, v0
	v_max_f32_e32 v1, 0, v66
	v_max_f32_e32 v2, 0, v50
	v_mul_f32_e32 v1, v1, v1
	v_mul_f32_e32 v2, v2, v2
	v_cvt_pk_bf16_f32 v1, v1, v1
	v_cvt_pk_bf16_f32 v2, v2, v2
	global_store_short v0, v1, s[2:3]
	global_store_short v0, v2, s[2:3] offset:64
	v_add_u32_e32 v0, 0x2000, v0
	v_max_f32_e32 v70, 0, v67
	v_max_f32_e32 v71, 0, v51
	v_mul_f32_e32 v70, v70, v70
	v_mul_f32_e32 v71, v71, v71
	v_cvt_pk_bf16_f32 v70, v70, v70
	v_cvt_pk_bf16_f32 v71, v71, v71
	global_store_short v0, v70, s[2:3]
	global_store_short v0, v71, s[2:3] offset:64
	v_add_u32_e32 v0, 0xa000, v0
	v_max_f32_e32 v1, 0, v20
	v_max_f32_e32 v2, 0, v4
	v_mul_f32_e32 v1, v1, v1
	v_mul_f32_e32 v2, v2, v2
	v_cvt_pk_bf16_f32 v1, v1, v1
	v_cvt_pk_bf16_f32 v2, v2, v2
	global_store_short v0, v1, s[2:3]
	global_store_short v0, v2, s[2:3] offset:64
	v_add_u32_e32 v0, 0x2000, v0
	v_max_f32_e32 v70, 0, v21
	v_max_f32_e32 v71, 0, v5
	v_mul_f32_e32 v70, v70, v70
	v_mul_f32_e32 v71, v71, v71
	v_cvt_pk_bf16_f32 v70, v70, v70
	v_cvt_pk_bf16_f32 v71, v71, v71
	global_store_short v0, v70, s[2:3]
	global_store_short v0, v71, s[2:3] offset:64
	v_add_u32_e32 v0, 0x2000, v0
	v_max_f32_e32 v1, 0, v22
	v_max_f32_e32 v2, 0, v6
	v_mul_f32_e32 v1, v1, v1
	v_mul_f32_e32 v2, v2, v2
	v_cvt_pk_bf16_f32 v1, v1, v1
	v_cvt_pk_bf16_f32 v2, v2, v2
	global_store_short v0, v1, s[2:3]
	global_store_short v0, v2, s[2:3] offset:64
	v_add_u32_e32 v0, 0x2000, v0
	v_max_f32_e32 v70, 0, v23
	v_max_f32_e32 v71, 0, v7
	v_mul_f32_e32 v70, v70, v70
	v_mul_f32_e32 v71, v71, v71
	v_cvt_pk_bf16_f32 v70, v70, v70
; DI int crow(int reg, int h) { return (reg & 3) + 8 * (reg >> 2) + 4 * h; }
; template <class Epi, class ColV>
; DI void gemm_tile(const bf16_t* __restrict__ A, int lda, const bf16_t* __restrict__ Bt, int ldb, int K, int m0, int n0, unsigned char* smem, Epi epi, ColV colv, const bf16_t* __restrict__ HYT = nullptr) {
;     ...
;     const float cv0 = colv(m0, n0 + 64 * wc + li), cv1 = colv(m0, n0 + 64 * wc + 32 + li);
; #pragma unroll
;     for (int mi = 0; mi < 2; ++mi)
; #pragma unroll
;         for (int ni = 0; ni < 2; ++ni)
; #pragma unroll
;             for (int reg = 0; reg < 16; ++reg)
;                 epi(m0 + 64 * wr + 32 * mi + crow(reg, lh), n0 + 64 * wc + 32 * ni + li, acc[mi][ni][reg], ni ? cv1 : cv0);
	v_cvt_pk_bf16_f32 v71, v71, v71
	global_store_short v0, v70, s[2:3]
	global_store_short v0, v71, s[2:3] offset:64
	v_add_u32_e32 v0, 0xa000, v0
	v_max_f32_e32 v1, 0, v24
	v_max_f32_e32 v2, 0, v8
	v_mul_f32_e32 v1, v1, v1
	v_mul_f32_e32 v2, v2, v2
	v_cvt_pk_bf16_f32 v1, v1, v1
	v_cvt_pk_bf16_f32 v2, v2, v2
	global_store_short v0, v1, s[2:3]
	global_store_short v0, v2, s[2:3] offset:64
	v_add_u32_e32 v0, 0x2000, v0
	v_max_f32_e32 v70, 0, v25
	v_max_f32_e32 v71, 0, v9
	v_mul_f32_e32 v70, v70, v70
	v_mul_f32_e32 v71, v71, v71
	v_cvt_pk_bf16_f32 v70, v70, v70
	v_cvt_pk_bf16_f32 v71, v71, v71
	global_store_short v0, v70, s[2:3]
	global_store_short v0, v71, s[2:3] offset:64
	v_add_u32_e32 v0, 0x2000, v0
	v_max_f32_e32 v1, 0, v26
	v_max_f32_e32 v2, 0, v10
	v_mul_f32_e32 v1, v1, v1
	v_mul_f32_e32 v2, v2, v2
	v_cvt_pk_bf16_f32 v1, v1, v1
	v_cvt_pk_bf16_f32 v2, v2, v2
	global_store_short v0, v1, s[2:3]
	global_store_short v0, v2, s[2:3] offset:64
	v_add_u32_e32 v0, 0x2000, v0
	v_max_f32_e32 v70, 0, v27
	v_max_f32_e32 v71, 0, v11
	v_mul_f32_e32 v70, v70, v70
	v_mul_f32_e32 v71, v71, v71
	v_cvt_pk_bf16_f32 v70, v70, v70
	v_cvt_pk_bf16_f32 v71, v71, v71
	global_store_short v0, v70, s[2:3]
	global_store_short v0, v71, s[2:3] offset:64
	v_add_u32_e32 v0, 0xa000, v0
	v_max_f32_e32 v1, 0, v28
	v_max_f32_e32 v2, 0, v12
	v_mul_f32_e32 v1, v1, v1
	v_mul_f32_e32 v2, v2, v2
	v_cvt_pk_bf16_f32 v1, v1, v1
	v_cvt_pk_bf16_f32 v2, v2, v2
	global_store_short v0, v1, s[2:3]
	global_store_short v0, v2, s[2:3] offset:64
	v_add_u32_e32 v0, 0x2000, v0
	v_max_f32_e32 v70, 0, v29
	v_max_f32_e32 v71, 0, v13
	v_mul_f32_e32 v70, v70, v70
	v_mul_f32_e32 v71, v71, v71
	v_cvt_pk_bf16_f32 v70, v70, v70
	v_cvt_pk_bf16_f32 v71, v71, v71
	global_store_short v0, v70, s[2:3]
	global_store_short v0, v71, s[2:3] offset:64
	v_add_u32_e32 v0, 0x2000, v0
	v_max_f32_e32 v1, 0, v30
	v_max_f32_e32 v2, 0, v14
	v_mul_f32_e32 v1, v1, v1
	v_mul_f32_e32 v2, v2, v2
	v_cvt_pk_bf16_f32 v1, v1, v1
	v_cvt_pk_bf16_f32 v2, v2, v2
	global_store_short v0, v1, s[2:3]
	global_store_short v0, v2, s[2:3] offset:64
	v_add_u32_e32 v0, 0x2000, v0
	v_max_f32_e32 v70, 0, v31
	v_max_f32_e32 v71, 0, v15
	v_mul_f32_e32 v70, v70, v70
	v_mul_f32_e32 v71, v71, v71
	v_cvt_pk_bf16_f32 v70, v70, v70
	v_cvt_pk_bf16_f32 v71, v71, v71
	global_store_short v0, v70, s[2:3]
	global_store_short v0, v71, s[2:3] offset:64
	v_add_u32_e32 v0, 0xa000, v0
	v_max_f32_e32 v1, 0, v32
	v_max_f32_e32 v2, 0, v16
	v_mul_f32_e32 v1, v1, v1
	v_mul_f32_e32 v2, v2, v2
	v_cvt_pk_bf16_f32 v1, v1, v1
	v_cvt_pk_bf16_f32 v2, v2, v2
	global_store_short v0, v1, s[2:3]
	global_store_short v0, v2, s[2:3] offset:64
	v_add_u32_e32 v0, 0x2000, v0
	v_max_f32_e32 v70, 0, v33
	v_max_f32_e32 v71, 0, v17
	v_mul_f32_e32 v70, v70, v70
	v_mul_f32_e32 v71, v71, v71
	v_cvt_pk_bf16_f32 v70, v70, v70
	v_cvt_pk_bf16_f32 v71, v71, v71
	global_store_short v0, v70, s[2:3]
	global_store_short v0, v71, s[2:3] offset:64
	v_add_u32_e32 v0, 0x2000, v0
	v_max_f32_e32 v1, 0, v34
	v_max_f32_e32 v2, 0, v18
	v_mul_f32_e32 v1, v1, v1
	v_mul_f32_e32 v2, v2, v2
	v_cvt_pk_bf16_f32 v1, v1, v1
	v_cvt_pk_bf16_f32 v2, v2, v2
	global_store_short v0, v1, s[2:3]
	global_store_short v0, v2, s[2:3] offset:64
	v_add_u32_e32 v0, 0x2000, v0
	v_max_f32_e32 v70, 0, v35
	v_max_f32_e32 v71, 0, v19
	v_mul_f32_e32 v70, v70, v70
	v_mul_f32_e32 v71, v71, v71
	v_cvt_pk_bf16_f32 v70, v70, v70
	v_cvt_pk_bf16_f32 v71, v71, v71
	global_store_short v0, v70, s[2:3]
	global_store_short v0, v71, s[2:3] offset:64
	s_add_i32 s37, s37, s36
	s_cmp_ge_i32 s37, s15
	s_cbranch_scc1 .Lff1_done
.LBB0_54:
	v_mov_b32_e32 v34, v168
	s_cmp_lt_u32 s37, 0x200
	s_cbranch_scc0 .Lff1_rowmap
	s_lshr_b32 s12, s37, 6
	s_and_b32 s13, s37, 63
	s_lshr_b32 s38, s12, 2
	s_lshl_b32 s38, s38, 3
	s_lshr_b32 s39, s13, 3
	s_add_u32 s38, s38, s39
	s_lshl_b32 s39, s38, 10
	s_or_b32 s39, s39, s76
	s_and_b32 s12, s12, 3
	s_lshl_b32 s12, s12, 3
	s_and_b32 s13, s13, 7
	s_add_u32 s13, s12, s13
	s_branch .Lff1_mapdone
.Lff1_rowmap:
	s_lshr_b32 s12, s37, 5
	s_lshl_b32 s12, s12, 10
	s_and_b32 s13, s37, 31
	s_or_b32 s39, s12, s76
; DI int get_tid() { int t = (int)__builtin_amdgcn_workitem_id_x(); asm volatile("" : "+v"(t)); return t; }
; DI f32x16 zero16() { f32x16 z; _Pragma("unroll") for (int i = 0; i < 16; ++i) z[i] = 0.f; return z; }
; template <class Epi, class ColV>
; DI void gemm_tile(const bf16_t* __restrict__ A, int lda, const bf16_t* __restrict__ Bt, int ldb, int K, int m0, int n0, unsigned char* smem, Epi epi, ColV colv, const bf16_t* __restrict__ HYT = nullptr) {
;     constexpr int LS = 72;
;     bf16_t* As = (bf16_t*)smem;
;     bf16_t* Bs = As + 2 * 128 * LS;
;     const int tid = get_tid(), lane = tid & 63, wave = tid >> 6, wr = wave >> 1, wc = wave & 1, li = lane & 31, lh = lane >> 5;
;     f32x16 acc[2][2];
; #pragma unroll
;     for (int a = 0; a < 2; ++a)
; #pragma unroll
;         for (int b = 0; b < 2; ++b) acc[a][b] = zero16();
;     u32x4 R0[8], R1[8];
;     const int nk = K >> 6;
;     auto gload = [&](u32x4 (&r)[8], int kt) {
; #pragma unroll
;         for (int i = 0; i < 4; ++i) { int id = tid + 256 * i, row = id >> 3, kc = id & 7;
;             if (HYT && kt >= 12) r[i] = *(const u32x4*)(HYT + (size_t)((kt - 12) * 64 + (id >> 4)) * NT + m0 + (id & 15) * 8);
;             else r[i] = *(const u32x4*)(A + (size_t)(m0 + row) * lda + kt * 64 + kc * 8);
;             r[4 + i] = *(const u32x4*)(Bt + (size_t)(n0 + row) * ldb + kt * 64 + kc * 8); }
;     };
;     ...
;     gload(R0, 0); gload(R1, 1);
;     sstore(R0, 0, 0); __syncthreads();
.Lff1_mapdone:
	v_add_u32_e32 v10, 0x100, v34
	v_add_u32_e32 v18, 0x200, v34
	v_add_u32_e32 v26, 0x300, v34
	s_lshl_b32 s38, s13, 7
	v_ashrrev_i32_e32 v35, 3, v34
	v_ashrrev_i32_e32 v36, 3, v10
	v_ashrrev_i32_e32 v37, 3, v18
	v_ashrrev_i32_e32 v38, 3, v26
	v_add_u32_e32 v0, s39, v35
	v_add_u32_e32 v6, s38, v35
	v_add_u32_e32 v10, s39, v36
	v_add_u32_e32 v14, s38, v36
	v_add_u32_e32 v18, s39, v37
	v_add_u32_e32 v22, s38, v37
	v_add_u32_e32 v26, s39, v38
	v_add_u32_e32 v30, s38, v38
	v_ashrrev_i32_e32 v1, 31, v0
	v_readlane_b32 s12, v252, 8
	v_ashrrev_i32_e32 v7, 31, v6
	v_ashrrev_i32_e32 v11, 31, v10
	v_ashrrev_i32_e32 v15, 31, v14
	v_ashrrev_i32_e32 v19, 31, v18
	v_ashrrev_i32_e32 v23, 31, v22
	v_ashrrev_i32_e32 v27, 31, v26
	v_ashrrev_i32_e32 v31, 31, v30
	v_lshlrev_b64 v[4:5], 11, v[0:1]
	v_readlane_b32 s13, v252, 9
	v_lshlrev_b32_e32 v2, 4, v34
	v_lshlrev_b64 v[6:7], 11, v[6:7]
	v_lshlrev_b64 v[10:11], 11, v[10:11]
	v_lshlrev_b64 v[14:15], 11, v[14:15]
	v_lshlrev_b64 v[18:19], 11, v[18:19]
	v_lshlrev_b64 v[22:23], 11, v[22:23]
	v_lshlrev_b64 v[26:27], 11, v[26:27]
	v_lshlrev_b64 v[30:31], 11, v[30:31]
	v_lshl_add_u64 v[0:1], s[12:13], 0, v[4:5]
	v_and_b32_e32 v2, 0x70, v2
	v_lshl_add_u64 v[8:9], s[10:11], 0, v[6:7]
	v_lshl_add_u64 v[12:13], s[12:13], 0, v[10:11]
	v_lshl_add_u64 v[16:17], s[10:11], 0, v[14:15]
	v_lshl_add_u64 v[20:21], s[12:13], 0, v[18:19]
	v_lshl_add_u64 v[24:25], s[10:11], 0, v[22:23]
	v_lshl_add_u64 v[28:29], s[12:13], 0, v[26:27]
	v_lshl_add_u64 v[32:33], s[10:11], 0, v[30:31]
	v_lshl_add_u64 v[0:1], v[0:1], 0, v[2:3]
	v_lshl_add_u64 v[8:9], v[8:9], 0, v[2:3]
	v_lshl_add_u64 v[12:13], v[12:13], 0, v[2:3]
	v_lshl_add_u64 v[16:17], v[16:17], 0, v[2:3]
	v_lshl_add_u64 v[20:21], v[20:21], 0, v[2:3]
	v_lshl_add_u64 v[24:25], v[24:25], 0, v[2:3]
	v_lshl_add_u64 v[28:29], v[28:29], 0, v[2:3]
	v_lshl_add_u64 v[32:33], v[32:33], 0, v[2:3]
	global_load_dwordx4 v[68:71], v[0:1], off
	global_load_dwordx4 v[72:75], v[8:9], off
	global_load_dwordx4 v[76:79], v[12:13], off
	global_load_dwordx4 v[80:83], v[16:17], off
	global_load_dwordx4 v[84:87], v[20:21], off
	global_load_dwordx4 v[92:95], v[24:25], off
	global_load_dwordx4 v[104:107], v[28:29], off
	global_load_dwordx4 v[112:115], v[32:33], off
	global_load_dwordx4 v[88:91], v[0:1], off offset:128
	global_load_dwordx4 v[96:99], v[8:9], off offset:128
	global_load_dwordx4 v[100:103], v[12:13], off offset:128
	global_load_dwordx4 v[108:111], v[16:17], off offset:128
	global_load_dwordx4 v[116:119], v[20:21], off offset:128
	global_load_dwordx4 v[120:123], v[24:25], off offset:128
	global_load_dwordx4 v[124:127], v[28:29], off offset:128
	global_load_dwordx4 v[128:131], v[32:33], off offset:128
	v_ashrrev_i32_e32 v0, 1, v34
	v_and_b32_e32 v151, 31, v34
	v_and_b32_e32 v193, 0xffffffc0, v0
	v_bfe_u32 v166, v34, 5, 1
	v_or_b32_e32 v0, v193, v151
	v_mul_lo_u32 v0, v0, s6
	v_lshlrev_b32_e32 v1, 4, v166
	v_add3_u32 v194, 0, v0, v1
	v_and_b32_e32 v0, 0x5f, v34
	v_mul_u32_u24_e32 v0, 0x90, v0
	v_and_b32_e32 v148, 64, v34
	v_add3_u32 v195, 0, v0, v1
	v_or_b32_e32 v0, 0x80, v151
	v_add_u32_e32 v8, v0, v193
	v_or_b32_e32 v0, v0, v148
	v_mul_u32_u24_e32 v0, 0x90, v0
	v_mul_lo_u32 v35, v35, s6
	v_mul_lo_u32 v36, v36, s6
	v_mul_lo_u32 v37, v37, s6
	v_mul_lo_u32 v38, v38, s6
	v_add3_u32 v197, 0, v0, v1
	v_add_u32_e32 v0, 0, v2
	v_mul_lo_u32 v8, v8, s6
	v_add_u32_e32 v198, v0, v35
	v_add_u32_e32 v199, v0, v36
	v_add_u32_e32 v200, v0, v37
	v_add_u32_e32 v201, v0, v38
	v_and_b32_e32 v0, 7, v34
	v_lshl_add_u64 v[144:145], s[26:27], 0, v[4:5]
	v_mov_b32_e32 v4, 0
	v_add3_u32 v167, 0, v35, v2
	v_add3_u32 v190, 0, v36, v2
	v_add3_u32 v191, 0, v37, v2
	v_add3_u32 v192, 0, v38, v2
	v_add3_u32 v196, 0, v8, v1
	v_lshlrev_b32_e32 v2, 4, v0
	v_lshl_add_u64 v[0:1], s[0:1], 0, v[30:31]
	v_lshl_add_u64 v[132:133], s[26:27], 0, v[26:27]
	v_lshl_add_u64 v[134:135], s[0:1], 0, v[22:23]
	v_lshl_add_u64 v[136:137], s[26:27], 0, v[18:19]
	v_lshl_add_u64 v[138:139], s[0:1], 0, v[14:15]
	v_lshl_add_u64 v[140:141], s[26:27], 0, v[10:11]
	v_lshl_add_u64 v[142:143], s[0:1], 0, v[6:7]
	s_mov_b32 s40, 0
	v_mov_b32_e32 v5, v4
	v_mov_b32_e32 v6, v4
	v_mov_b32_e32 v7, v4
	v_mov_b32_e32 v8, v4
	v_mov_b32_e32 v9, v4
	v_mov_b32_e32 v10, v4
	v_mov_b32_e32 v11, v4
	v_mov_b32_e32 v12, v4
	v_mov_b32_e32 v13, v4
	v_mov_b32_e32 v14, v4
	v_mov_b32_e32 v15, v4
	v_mov_b32_e32 v16, v4
	v_mov_b32_e32 v17, v4
	v_mov_b32_e32 v18, v4
	v_mov_b32_e32 v19, v4
	v_mov_b32_e32 v20, v4
	v_mov_b32_e32 v21, v4
	v_mov_b32_e32 v22, v4
	v_mov_b32_e32 v23, v4
	v_mov_b32_e32 v24, v4
	v_mov_b32_e32 v25, v4
	v_mov_b32_e32 v26, v4
	v_mov_b32_e32 v27, v4
	v_mov_b32_e32 v28, v4
	v_mov_b32_e32 v29, v4
	v_mov_b32_e32 v30, v4
	v_mov_b32_e32 v31, v4
	v_mov_b32_e32 v32, v4
	v_mov_b32_e32 v33, v4
	v_mov_b32_e32 v34, v4
	v_mov_b32_e32 v35, v4
	v_mov_b32_e32 v36, v4
	v_mov_b32_e32 v37, v4
	v_mov_b32_e32 v38, v4
	v_mov_b32_e32 v39, v4
	v_mov_b32_e32 v40, v4
	v_mov_b32_e32 v41, v4
	v_mov_b32_e32 v42, v4
	v_mov_b32_e32 v43, v4
	v_mov_b32_e32 v44, v4
	v_mov_b32_e32 v45, v4
	v_mov_b32_e32 v46, v4
	v_mov_b32_e32 v47, v4
	v_mov_b32_e32 v48, v4
	v_mov_b32_e32 v49, v4
	v_mov_b32_e32 v50, v4
	v_mov_b32_e32 v51, v4
	s_waitcnt vmcnt(33)
	v_mov_b32_e32 v52, v4
	s_waitcnt vmcnt(32)
	v_mov_b32_e32 v53, v4
	v_mov_b32_e32 v54, v4
	v_mov_b32_e32 v55, v4
	v_mov_b32_e32 v56, v4
	v_mov_b32_e32 v57, v4
	v_mov_b32_e32 v58, v4
	v_mov_b32_e32 v59, v4
	v_mov_b32_e32 v60, v4
	v_mov_b32_e32 v61, v4
	v_mov_b32_e32 v62, v4
	v_mov_b32_e32 v63, v4
	v_mov_b32_e32 v64, v4
	v_mov_b32_e32 v65, v4
	v_mov_b32_e32 v66, v4
	v_mov_b32_e32 v67, v4
	s_waitcnt vmcnt(15)
	ds_write_b128 v167, v[68:71]
	s_waitcnt vmcnt(14)
	ds_write_b128 v167, v[72:75] offset:36864
	s_waitcnt vmcnt(13)
	ds_write_b128 v190, v[76:79]
	s_waitcnt vmcnt(12)
	ds_write_b128 v190, v[80:83] offset:36864
	s_waitcnt vmcnt(11)
	ds_write_b128 v191, v[84:87]
	s_waitcnt vmcnt(10)
	ds_write_b128 v191, v[92:95] offset:36864
	s_waitcnt vmcnt(9)
	ds_write_b128 v192, v[104:107]
	s_waitcnt vmcnt(8)
	ds_write_b128 v192, v[112:115] offset:36864
	s_waitcnt lgkmcnt(0)
	s_barrier
	s_branch .LBB0_56

; DI bf16_t f2bf(float x) { unsigned r; asm("v_cvt_pk_bf16_f32 %0, %1, %1" : "=v"(r) : "v"(x)); return (bf16_t)r; }
; #define XCD_TILE_LOOP(MT, NTN, m_, n_) for (int lt_ = (bid >> 3), m_ = 0, n_ = 0; (lt_ < ((MT) >> 3) * (NTN)) && ((m_ = (bid & 7) + 8 * (lt_ / (NTN))), (n_ = lt_ % (NTN)), true); lt_ += (G >> 3))
;     ...
;     case 10: {
;         bf16_t* HID = (bf16_t*)(p.ws + WS_HID);
;         auto epi = [&](int r, int c, float v, float) { const float a = fmaxf(v, 0.f); HID[(size_t)r * 4096 + c] = f2bf(a * a); };
;         auto nocol = [&](int, int) { return 0.f; };
;         XCD_TILE_LOOP((layer == 0 ? NT : NL) / 128, 32, tm, tn) gemm_tile((const bf16_t*)(p.ws + WS_H), 1024, (const bf16_t*)(p.ws + wbase(layer) + W_FF1), 1024, 1024, tm * 128, tn * 128, smem, epi, nocol);
;     } break;
.Lff1_done:
	s_cmp_lt_u32 s74, 12
	s_mov_b32 s0, 0x40000
	s_cselect_b32 s0, s0, 0xe4b6000
	s_add_u32 s0, s26, s0
	s_addc_u32 s1, s27, 0
	s_add_u32 s0, s0, 0xe80000
	s_addc_u32 s1, s1, 0
	v_readlane_b32 s10, v252, 0
	s_nop 0
	s_lshl_b32 s10, s10, 14
	v_lshl_add_u32 v202, v168, 6, s10
	global_load_dword v203, v202, s[0:1]

; DI int get_tid() { int t = (int)__builtin_amdgcn_workitem_id_x(); asm volatile("" : "+v"(t)); return t; }
; DI void norm_rows(const Params& p, int layer, int which  , int nrows, bool from_input) {
;     const int lane = get_tid() & 63, gw = blockIdx.x * 4 + (get_tid() >> 6), NGW = gridDim.x * 4;
;     const float* g = p.in[which ? I_GMLP : I_GMIX] + layer * 1024;
;     const float* MOD = (const float*)(p.ws + WS_MOD) + (size_t)layer * 5 * 6144;
;     bf16_t* H = (bf16_t*)(p.ws + WS_H);
;     const int rpw = (nrows + NGW - 1) / NGW, rbeg = gw * rpw, rend = min(nrows, rbeg + rpw);
;     f32x4 ga[4], sb[4]; int mb_cur = -1;
.LBB0_63:
	s_andn2_b64 vcc, exec, s[0:1]
	s_cbranch_vccnz .LBB0_74
	s_cmp_lt_u32 s74, 12
	s_mov_b32 s0, 0x40000
	s_cselect_b32 s0, s0, 0xe4b6000
	s_add_u32 s0, s26, s0
	s_addc_u32 s1, s27, 0
	s_add_u32 s0, s0, 0x680000
	s_addc_u32 s1, s1, 0
	v_readlane_b32 s10, v252, 0
	s_nop 0
	s_lshl_b32 s10, s10, 14
	v_lshl_add_u32 v202, v168, 6, s10
	global_load_dword v203, v202, s[0:1]
	s_add_i32 s0, s74, 11
	s_cmp_lt_u32 s0, 23
	s_movk_i32 s0, 0x4400
	v_readlane_b32 s1, v255, 27
	s_cselect_b32 s0, s0, 0x4000
	s_lshl_b32 s1, s1, 2
	s_abs_i32 s10, s1
	v_cvt_f32_u32_e32 v2, s10
	v_mov_b32_e32 v0, v168
	v_mov_b32_e32 v1, v168
	v_rcp_iflag_f32_e32 v2, v2
	v_readlane_b32 s11, v252, 7
	v_ashrrev_i32_e32 v1, 6, v1
	v_mul_f32_e32 v2, 0x4f7ffffe, v2
	v_cvt_u32_f32_e32 v2, v2
	v_add_u32_e32 v1, s11, v1
	s_add_i32 s11, s0, s1
	s_add_i32 s12, s11, -1
	s_sub_i32 s11, 1, s11
	s_xor_b32 s1, s12, s1
	s_max_i32 s11, s12, s11
	s_sub_i32 s12, 0, s10
	v_readfirstlane_b32 s13, v2
	s_mul_i32 s12, s12, s13
	s_mul_hi_u32 s12, s13, s12
	s_add_i32 s13, s13, s12
	s_mul_hi_u32 s12, s11, s13
	s_mul_i32 s13, s12, s10
	s_sub_i32 s11, s11, s13
	s_ashr_i32 s1, s1, 31
	s_add_i32 s13, s12, 1
	s_sub_i32 s15, s11, s10
	s_cmp_ge_u32 s11, s10
	s_cselect_b32 s12, s13, s12
	s_cselect_b32 s11, s15, s11
	s_add_i32 s13, s12, 1
	s_cmp_ge_u32 s11, s10
	s_cselect_b32 s10, s13, s12
	s_xor_b32 s10, s10, s1
	s_sub_i32 s1, s10, s1
	s_waitcnt vmcnt(17)
	v_mul_lo_u32 v52, v1, s1
	v_add_u32_e32 v1, s1, v52
	v_min_i32_e32 v55, s0, v1
	v_cmp_lt_i32_e32 vcc, v52, v55
	s_and_saveexec_b64 s[10:11], vcc
	s_cbranch_execz .LBB0_73
	v_lshlrev_b32_e32 v1, 2, v0
	v_and_b32_e32 v54, 0xfc, v1
	v_and_b32_e32 v1, 64, v182
	v_add_u32_e32 v1, 64, v1
	v_xor_b32_e32 v2, 1, v182
	v_cmp_lt_i32_e32 vcc, v2, v1
	v_readlane_b32 s0, v255, 28
	v_readlane_b32 s1, v255, 29
	v_cndmask_b32_e32 v2, v182, v2, vcc
	v_lshlrev_b32_e32 v68, 2, v2
	v_xor_b32_e32 v2, 2, v182
	v_cmp_lt_i32_e32 vcc, v2, v1
	s_lshl_b32 s0, s0, 10
	s_ashr_i32 s1, s0, 31
	v_cndmask_b32_e32 v2, v182, v2, vcc
	v_lshlrev_b32_e32 v69, 2, v2
	v_xor_b32_e32 v2, 4, v182
	v_cmp_lt_i32_e32 vcc, v2, v1
	v_readlane_b32 s36, v254, 55
	s_lshl_b64 s[0:1], s[0:1], 2
	v_cndmask_b32_e32 v2, v182, v2, vcc
	v_lshlrev_b32_e32 v70, 2, v2
	v_xor_b32_e32 v2, 8, v182
	v_cmp_lt_i32_e32 vcc, v2, v1
	v_readlane_b32 s50, v255, 5
	v_readlane_b32 s51, v255, 6
	v_cndmask_b32_e32 v2, v182, v2, vcc
	v_lshlrev_b32_e32 v71, 2, v2
	v_xor_b32_e32 v2, 16, v182
	v_cmp_lt_i32_e32 vcc, v2, v1
	s_add_u32 s0, s50, s0
	s_waitcnt vmcnt(16)
	v_ashrrev_i32_e32 v53, 31, v52
	v_cndmask_b32_e32 v2, v182, v2, vcc
	v_lshlrev_b32_e32 v72, 2, v2
	v_xor_b32_e32 v2, 32, v182
	v_cmp_lt_i32_e32 vcc, v2, v1
	s_addc_u32 s1, s51, s1
	v_lshlrev_b64 v[4:5], 12, v[52:53]
	v_cndmask_b32_e32 v1, v182, v2, vcc
	v_lshlrev_b32_e32 v2, 2, v54
	v_lshl_add_u64 v[56:57], s[0:1], 0, v[2:3]
	v_lshl_add_u64 v[58:59], s[24:25], 0, v[4:5]
	v_lshlrev_b64 v[4:5], 11, v[52:53]
	v_and_b32_e32 v0, 63, v0
	v_readlane_b32 s0, v252, 8
	s_add_u32 s9, s26, s9
	v_lshl_or_b32 v4, v0, 3, v4
	v_readlane_b32 s1, v252, 9
	s_addc_u32 s8, s27, s8
	v_or_b32_e32 v16, 0x100, v54
	v_or_b32_e32 v18, 0x200, v54
	v_lshl_add_u64 v[60:61], s[0:1], 0, v[4:5]
	v_mov_b32_e32 v4, v3
	v_mov_b32_e32 v5, v3
	v_mov_b32_e32 v6, v3
	v_mov_b32_e32 v7, v3
	v_mov_b32_e32 v8, v3
	v_mov_b32_e32 v9, v3
	v_mov_b32_e32 v10, v3
	v_mov_b32_e32 v11, v3
	v_mov_b32_e32 v12, v3
	v_mov_b32_e32 v13, v3
	v_mov_b32_e32 v14, v3
	v_mov_b32_e32 v15, v3
	s_add_u32 s12, s9, 0x7000
	v_lshlrev_b32_e32 v73, 2, v1
	v_or_b32_e32 v20, 0x300, v54
	v_mov_b32_e32 v0, v3
	v_mov_b32_e32 v1, v3
	v_mov_b32_e32 v2, v3
	v_lshlrev_b32_e32 v62, 2, v16
	v_lshlrev_b32_e32 v64, 2, v18
	v_mov_b64_e32 v[18:19], v[14:15]
	s_addc_u32 s13, s8, 0
	v_mov_b32_e32 v63, -1
	s_mov_b64 s[18:19], 0
	v_lshlrev_b32_e32 v66, 2, v20
	v_mov_b64_e32 v[16:17], v[12:13]
	v_mov_b64_e32 v[14:15], v[10:11]
	v_mov_b64_e32 v[12:13], v[8:9]
	v_mov_b64_e32 v[10:11], v[6:7]
	v_mov_b64_e32 v[8:9], v[4:5]
	v_mov_b64_e32 v[6:7], v[2:3]
	v_mov_b64_e32 v[4:5], v[0:1]
	v_readlane_b32 s37, v254, 56
	v_readlane_b32 s38, v254, 57
	v_readlane_b32 s39, v254, 58
	v_readlane_b32 s40, v254, 59
	v_readlane_b32 s41, v254, 60
	v_readlane_b32 s42, v254, 61
	v_readlane_b32 s43, v254, 62
	v_readlane_b32 s44, v254, 63
	v_readlane_b32 s45, v255, 0
	v_readlane_b32 s46, v255, 1
	v_readlane_b32 s47, v255, 2
	v_readlane_b32 s48, v255, 3
	v_readlane_b32 s49, v255, 4
	s_branch .LBB0_67

; DI int get_tid() { int t = (int)__builtin_amdgcn_workitem_id_x(); asm volatile("" : "+v"(t)); return t; }
;     ...
;         for (;;) {
;             __syncthreads();
;             if (get_tid() == 0) st[2] = sub ? 0xffffffffu : atomicAdd(ctr, 1u);
;             __syncthreads();
;             const int it = (int)st[2];
;             if (it < 0 || it >= n5) break;
;             if (it < n1) hyena_lat_item(p, layer, it, smem);
;             else if (it < n2) { const int j = it - n1, bh = j >> 5, qt = j & 31; attn_item(p, (const bf16_t*)(p.ws + WS_Q) + (size_t)bh * SEQ * 96, bh, qt * 128, NKEY, (bh / 6) * SEQ, smem); }
.LBB0_307:
	s_or_b64 exec, exec, s[10:11]
	s_waitcnt vmcnt(0)
	v_readfirstlane_b32 s8, v1
	s_nop 1
	s_sub_u32 s9, s8, 0x200
	s_cmp_lt_u32 s9, 0x300
	s_cbranch_scc0 .Lattn_xcd_done
	s_getreg_b32 s9, hwreg(HW_REG_XCC_ID, 0, 4)
	s_and_b32 s9, s9, 7
	s_mov_b32 s12, 0
.Lattn_xcd_try:
	v_readlane_b32 s10, v255, 38
	v_readlane_b32 s11, v255, 39
	s_lshl_b32 s13, s9, 8
	s_add_u32 s10, s10, s13
	s_addc_u32 s11, s11, 0
	v_mov_b32_e32 v1, 1
	s_nop 4
	global_atomic_add v1, v3, v1, s[10:11] offset:1088 sc0
	s_waitcnt vmcnt(0)
	v_readfirstlane_b32 s13, v1
	s_nop 1
	s_cmp_lt_u32 s13, 0x60
	s_cbranch_scc1 .Lattn_xcd_got
	s_add_u32 s9, s9, 1
	s_and_b32 s9, s9, 7
	s_add_u32 s12, s12, 1
	s_cmp_lt_u32 s12, 8
	s_cbranch_scc1 .Lattn_xcd_try
	s_branch .Lattn_xcd_done
.Lattn_xcd_got:
	s_lshr_b32 s10, s13, 5
	s_lshl_b32 s10, s10, 3
	s_add_u32 s10, s10, s9
	s_lshl_b32 s10, s10, 5
	s_and_b32 s13, s13, 31
	s_add_u32 s10, s10, s13
	s_add_u32 s8, s10, 0x200
.Lattn_xcd_done:
	v_add_u32_e32 v0, s8, v0
	v_readlane_b32 s8, v254, 48
	s_nop 1
	v_mov_b32_e32 v1, s8
	ds_write_b32 v1, v0

; #define MFMA(a, b, c) __builtin_amdgcn_mfma_f32_32x32x16_bf16((a), (b), (c), 0, 0, 0)
; DI f32x16 zero16() { f32x16 z; _Pragma("unroll") for (int i = 0; i < 16; ++i) z[i] = 0.f; return z; }
; DI void attn_item(const Params& p, const bf16_t* Qbase  , int bh, int q0, int nkeys, int out_row0, unsigned char* smem) {
;     ...
;     for (int kt = 0; kt < nkt; ++kt) {
;         const int buf = kt & 1;
;         if (kt + 1 < nkt) gload(kt + 1);
;         __builtin_amdgcn_sched_barrier(0);
;         f32x16 s0 = zero16(), s1 = zero16();
;         const bf16_t* kb = Ks + (buf * 64 + li) * KS + 8 * lh;
; #pragma unroll
;         for (int ks = 0; ks < 6; ++ks) { s0 = MFMA(ld8(kb + 16 * ks), qf[ks], s0); s1 = MFMA(ld8(kb + 32 * KS + 16 * ks), qf[ks], s1); }
;         float mx = fmaxf(s0[0], s1[0]);
; #pragma unroll
;         for (int r = 1; r < 16; ++r) mx = fmaxf(fmaxf(mx, s0[r]), s1[r]);
;         mx = fmaxf(mx, __shfl_xor(mx, 32));
;         const float mn = fmaxf(m, mx);
;         if (__any(mn > m)) {
;             const float corr = __builtin_amdgcn_exp2f((m - mn) * scl);
;             l *= corr;
; #pragma unroll
;             for (int r = 0; r < 16; ++r) { o0[r] *= corr; o1[r] *= corr; }
;             m = mn;
;         }
;         const float nb = -m * scl;
.LBB0_414:
	v_lshl_add_u64 v[140:141], s[26:27], 0, v[122:123]
	v_lshl_add_u64 v[142:143], s[26:27], 0, v[124:125]
	global_load_dwordx4 v[108:111], v[140:141], off
	global_load_dwordx4 v[104:107], v[142:143], off
	v_lshl_add_u64 v[140:141], s[26:27], 0, v[126:127]
	v_lshl_add_u64 v[142:143], s[26:27], 0, v[118:119]
	global_load_dwordx4 v[100:103], v[140:141], off
	global_load_dwordx4 v[96:99], v[142:143], off
	v_lshl_add_u64 v[140:141], s[26:27], 0, v[120:121]
	global_load_dwordx4 v[92:95], v[140:141], off
	s_and_b32 s9, s8, 64
	v_or_b32_e32 v138, s9, v1
	v_mad_u32_u24 v137, v138, s37, v135
	ds_read_b128 v[202:205], v137
	ds_read_b128 v[206:209], v137 offset:6656
	ds_read_b128 v[210:213], v137 offset:32
	ds_read_b128 v[214:217], v137 offset:6688
	ds_read_b128 v[218:221], v137 offset:64
	s_waitcnt lgkmcnt(4)
	v_mfma_f32_32x32x16_bf16 v[36:51], v[202:205], v[88:91], 0
	ds_read_b128 v[202:205], v137 offset:6720
	s_waitcnt lgkmcnt(4)
	v_mfma_f32_32x32x16_bf16 v[52:67], v[206:209], v[88:91], 0
	ds_read_b128 v[206:209], v137 offset:96
	s_waitcnt lgkmcnt(4)
	v_mfma_f32_32x32x16_bf16 v[36:51], v[210:213], v[84:87], v[36:51]
	ds_read_b128 v[210:213], v137 offset:6752
	s_waitcnt lgkmcnt(4)
	v_mfma_f32_32x32x16_bf16 v[52:67], v[214:217], v[84:87], v[52:67]
	ds_read_b128 v[214:217], v137 offset:128
	s_waitcnt lgkmcnt(4)
	v_mfma_f32_32x32x16_bf16 v[36:51], v[218:221], v[80:83], v[36:51]
	ds_read_b128 v[218:221], v137 offset:6784
	s_waitcnt lgkmcnt(4)
	v_mfma_f32_32x32x16_bf16 v[52:67], v[202:205], v[80:83], v[52:67]
	ds_read_b128 v[202:205], v137 offset:160
	s_waitcnt lgkmcnt(4)
	v_mfma_f32_32x32x16_bf16 v[36:51], v[206:209], v[76:79], v[36:51]
	ds_read_b128 v[206:209], v137 offset:6816
	s_waitcnt lgkmcnt(4)
	v_mfma_f32_32x32x16_bf16 v[52:67], v[210:213], v[76:79], v[52:67]
	s_waitcnt lgkmcnt(3)
	v_mfma_f32_32x32x16_bf16 v[36:51], v[214:217], v[72:75], v[36:51]
	s_waitcnt lgkmcnt(2)
	v_mfma_f32_32x32x16_bf16 v[52:67], v[218:221], v[72:75], v[52:67]
	s_waitcnt lgkmcnt(1)
	v_mfma_f32_32x32x16_bf16 v[36:51], v[202:205], v[68:71], v[36:51]
	s_waitcnt lgkmcnt(0)
	v_mfma_f32_32x32x16_bf16 v[52:67], v[206:209], v[68:71], v[52:67]
	s_movk_i32 s12, 0x88
	v_mad_u32_u24 v151, v138, s12, v117
	v_add_u32_e32 v148, 0x6800, v151
	v_add_u32_e32 v151, 0x7800, v151
	s_nop 7
	v_max3_f32 v137, v36, v37, v38
	v_max3_f32 v139, v52, v53, v54
	v_max3_f32 v137, v137, v39, v40
	v_max3_f32 v139, v139, v55, v56
	v_max3_f32 v137, v137, v41, v42
	v_max3_f32 v139, v139, v57, v58
	v_max3_f32 v137, v137, v43, v44
	v_max3_f32 v139, v139, v59, v60
	v_max3_f32 v137, v137, v45, v46
	v_max3_f32 v139, v139, v61, v62
	v_max3_f32 v137, v137, v47, v48
	v_max3_f32 v139, v139, v63, v64
	v_max3_f32 v137, v137, v49, v50
	v_max3_f32 v139, v139, v65, v66
	v_max3_f32 v137, v137, v51, v139
	v_max_f32_e32 v137, v137, v67
	ds_bpermute_b32 v139, v128, v137
	s_waitcnt lgkmcnt(0)
	v_max3_f32 v137, v136, v137, v139
	v_cmp_gt_f32_e32 vcc, v137, v136
	s_cbranch_vccz .Lattn_keep
	v_sub_f32_e32 v136, v136, v137
	v_mul_f32_e32 v136, 0x3e16c740, v136
	v_exp_f32_e32 v136, v136
	s_nop 0
	v_pk_mul_f32 v[4:5], v[4:5], v[136:137] op_sel_hi:[1,0]
	v_pk_mul_f32 v[6:7], v[6:7], v[136:137] op_sel_hi:[1,0]
	v_pk_mul_f32 v[8:9], v[8:9], v[136:137] op_sel_hi:[1,0]
	v_pk_mul_f32 v[10:11], v[10:11], v[136:137] op_sel_hi:[1,0]
	v_pk_mul_f32 v[12:13], v[12:13], v[136:137] op_sel_hi:[1,0]
	v_pk_mul_f32 v[14:15], v[14:15], v[136:137] op_sel_hi:[1,0]
	v_pk_mul_f32 v[16:17], v[16:17], v[136:137] op_sel_hi:[1,0]
	v_pk_mul_f32 v[18:19], v[18:19], v[136:137] op_sel_hi:[1,0]
	v_pk_mul_f32 v[20:21], v[20:21], v[136:137] op_sel_hi:[1,0]
	v_pk_mul_f32 v[22:23], v[22:23], v[136:137] op_sel_hi:[1,0]
	v_pk_mul_f32 v[24:25], v[24:25], v[136:137] op_sel_hi:[1,0]
	v_pk_mul_f32 v[26:27], v[26:27], v[136:137] op_sel_hi:[1,0]
	v_pk_mul_f32 v[28:29], v[28:29], v[136:137] op_sel_hi:[1,0]
	v_pk_mul_f32 v[30:31], v[30:31], v[136:137] op_sel_hi:[1,0]
	v_pk_mul_f32 v[32:33], v[32:33], v[136:137] op_sel_hi:[1,0]
	v_pk_mul_f32 v[34:35], v[34:35], v[136:137] op_sel_hi:[1,0]
	v_mul_f32_e32 v0, v0, v136
; #define MFMA(a, b, c) __builtin_amdgcn_mfma_f32_32x32x16_bf16((a), (b), (c), 0, 0, 0)
; DI void attn_item(const Params& p, const bf16_t* Qbase  , int bh, int q0, int nkeys, int out_row0, unsigned char* smem) {
;     ...
;             const float corr = __builtin_amdgcn_exp2f((m - mn) * scl);
;             l *= corr;
; #pragma unroll
;             for (int r = 0; r < 16; ++r) { o0[r] *= corr; o1[r] *= corr; }
;             m = mn;
;         }
;         const float nb = -m * scl;
;         float sum0 = 0.f, sum1 = 0.f;
; #pragma unroll
;         for (int r = 0; r < 16; ++r) { s0[r] = __builtin_amdgcn_exp2f(fmaf(s0[r], scl, nb)); s1[r] = __builtin_amdgcn_exp2f(fmaf(s1[r], scl, nb)); sum0 += s0[r]; sum1 += s1[r]; }
;         float sum = sum0 + sum1;
;         sum += __shfl_xor(sum, 32);
;         l += sum;
;         bf16x8 pf[2][2];
;         pf[0][0] = pack8(s0[0], s0[1], s0[2], s0[3], s0[4], s0[5], s0[6], s0[7]); pf[0][1] = pack8(s0[8], s0[9], s0[10], s0[11], s0[12], s0[13], s0[14], s0[15]);
;         pf[1][0] = pack8(s1[0], s1[1], s1[2], s1[3], s1[4], s1[5], s1[6], s1[7]); pf[1][1] = pack8(s1[8], s1[9], s1[10], s1[11], s1[12], s1[13], s1[14], s1[15]);
;         const bf16_t* vb = Vs + (buf * 64 + li) * VS + 4 * lh;
; #pragma unroll
;         for (int j = 0; j < 2; ++j)
; #pragma unroll
;             for (int s = 0; s < 2; ++s) {
;                 const int ko = 32 * j + 16 * s;
;                 o0 = MFMA(ld4x2(vb + ko, vb + ko + 8), pf[j][s], o0);
;                 o1 = MFMA(ld4x2(vb + 32 * VS + ko, vb + 32 * VS + ko + 8), pf[j][s], o1);
;             }
;         __builtin_amdgcn_sched_barrier(0);
;         if (kt + 1 < nkt) sstore(buf ^ 1);
;         __syncthreads();
.Lattn_keep:
	v_mul_f32_e32 v136, 0xbe16c740, v137
	v_fmamk_f32 v36, v36, 0x3e16c740, v136
	v_fmamk_f32 v37, v37, 0x3e16c740, v136
	v_exp_f32_e32 v36, v36
	v_fmamk_f32 v38, v38, 0x3e16c740, v136
	v_exp_f32_e32 v37, v37
	v_fmamk_f32 v39, v39, 0x3e16c740, v136
	v_exp_f32_e32 v38, v38
	v_fmamk_f32 v40, v40, 0x3e16c740, v136
	v_exp_f32_e32 v39, v39
	v_fmamk_f32 v41, v41, 0x3e16c740, v136
	v_exp_f32_e32 v40, v40
	v_fmamk_f32 v42, v42, 0x3e16c740, v136
	v_exp_f32_e32 v41, v41
	v_fmamk_f32 v43, v43, 0x3e16c740, v136
	v_exp_f32_e32 v42, v42
	v_fmamk_f32 v44, v44, 0x3e16c740, v136
	v_exp_f32_e32 v43, v43
	v_fmamk_f32 v45, v45, 0x3e16c740, v136
	v_exp_f32_e32 v44, v44
	v_fmamk_f32 v46, v46, 0x3e16c740, v136
	v_exp_f32_e32 v45, v45
	v_fmamk_f32 v47, v47, 0x3e16c740, v136
	v_exp_f32_e32 v46, v46
	v_fmamk_f32 v48, v48, 0x3e16c740, v136
	v_exp_f32_e32 v47, v47
	v_fmamk_f32 v49, v49, 0x3e16c740, v136
	v_exp_f32_e32 v48, v48
	v_fmamk_f32 v50, v50, 0x3e16c740, v136
	v_exp_f32_e32 v49, v49
	v_fmamk_f32 v51, v51, 0x3e16c740, v136
	v_exp_f32_e32 v50, v50
	v_fmamk_f32 v52, v52, 0x3e16c740, v136
	v_exp_f32_e32 v51, v51
	v_fmamk_f32 v53, v53, 0x3e16c740, v136
	v_exp_f32_e32 v52, v52
	v_fmamk_f32 v54, v54, 0x3e16c740, v136
	v_exp_f32_e32 v53, v53
	v_fmamk_f32 v55, v55, 0x3e16c740, v136
	v_exp_f32_e32 v54, v54
	v_fmamk_f32 v56, v56, 0x3e16c740, v136
	v_exp_f32_e32 v55, v55
	v_fmamk_f32 v57, v57, 0x3e16c740, v136
	v_exp_f32_e32 v56, v56
	v_fmamk_f32 v58, v58, 0x3e16c740, v136
	v_exp_f32_e32 v57, v57
	v_fmamk_f32 v59, v59, 0x3e16c740, v136
	v_exp_f32_e32 v58, v58
	v_fmamk_f32 v60, v60, 0x3e16c740, v136
	v_exp_f32_e32 v59, v59
	v_fmamk_f32 v61, v61, 0x3e16c740, v136
	v_exp_f32_e32 v60, v60
	v_fmamk_f32 v62, v62, 0x3e16c740, v136
	v_exp_f32_e32 v61, v61
	v_fmamk_f32 v63, v63, 0x3e16c740, v136
	v_exp_f32_e32 v62, v62
	v_fmamk_f32 v64, v64, 0x3e16c740, v136
	v_exp_f32_e32 v63, v63
	v_fmamk_f32 v65, v65, 0x3e16c740, v136
	v_exp_f32_e32 v64, v64
	v_fmamk_f32 v66, v66, 0x3e16c740, v136
	v_exp_f32_e32 v65, v65
	v_fmamk_f32 v67, v67, 0x3e16c740, v136
	v_exp_f32_e32 v66, v66
	v_exp_f32_e32 v67, v67
	v_pk_add_f32 v[138:139], v[36:37], v[38:39]
	v_pk_add_f32 v[152:153], v[52:53], v[54:55]
	v_pk_add_f32 v[138:139], v[138:139], v[40:41]
	v_pk_add_f32 v[152:153], v[152:153], v[56:57]
	v_pk_add_f32 v[138:139], v[138:139], v[42:43]
	v_pk_add_f32 v[152:153], v[152:153], v[58:59]
	v_pk_add_f32 v[138:139], v[138:139], v[44:45]
	v_pk_add_f32 v[152:153], v[152:153], v[60:61]
	v_pk_add_f32 v[138:139], v[138:139], v[46:47]
	v_pk_add_f32 v[152:153], v[152:153], v[62:63]
	v_pk_add_f32 v[138:139], v[138:139], v[48:49]
	v_pk_add_f32 v[152:153], v[152:153], v[64:65]
	v_pk_add_f32 v[138:139], v[138:139], v[50:51]
	v_pk_add_f32 v[152:153], v[152:153], v[66:67]
	v_cvt_pk_bf16_f32 v140, v52, v53
	v_cvt_pk_bf16_f32 v141, v54, v55
	v_cvt_pk_bf16_f32 v142, v56, v57
	v_cvt_pk_bf16_f32 v143, v58, v59
	v_cvt_pk_bf16_f32 v144, v60, v61
	v_cvt_pk_bf16_f32 v145, v62, v63
	v_cvt_pk_bf16_f32 v146, v64, v65
	v_cvt_pk_bf16_f32 v147, v66, v67
	ds_read2_b64 v[52:55], v148 offset1:2
	ds_read2_b64 v[56:59], v151 offset0:32 offset1:34
	ds_read2_b64 v[60:63], v148 offset0:4 offset1:6
	ds_read2_b64 v[64:67], v151 offset0:36 offset1:38
	v_cvt_pk_bf16_f32 v36, v36, v37
	v_cvt_pk_bf16_f32 v37, v38, v39
	v_cvt_pk_bf16_f32 v38, v40, v41
	v_cvt_pk_bf16_f32 v39, v42, v43
	v_cvt_pk_bf16_f32 v40, v44, v45
	v_cvt_pk_bf16_f32 v41, v46, v47
	v_cvt_pk_bf16_f32 v42, v48, v49
	v_cvt_pk_bf16_f32 v43, v50, v51
	v_pk_add_f32 v[138:139], v[138:139], v[152:153]
	v_add_f32_e32 v138, v138, v139
	ds_bpermute_b32 v139, v128, v138
	s_waitcnt lgkmcnt(4)
	v_mfma_f32_32x32x16_bf16 v[4:19], v[52:55], v[36:39], v[4:19]
	ds_read2_b64 v[52:55], v148 offset0:8 offset1:10
	s_waitcnt lgkmcnt(4)
	v_mfma_f32_32x32x16_bf16 v[20:35], v[56:59], v[36:39], v[20:35]
	ds_read2_b64 v[56:59], v151 offset0:40 offset1:42
	s_waitcnt lgkmcnt(4)
	v_mfma_f32_32x32x16_bf16 v[4:19], v[60:63], v[40:43], v[4:19]
	ds_read2_b64 v[60:63], v148 offset0:12 offset1:14
	s_waitcnt lgkmcnt(4)
	v_mfma_f32_32x32x16_bf16 v[20:35], v[64:67], v[40:43], v[20:35]
	ds_read2_b64 v[64:67], v151 offset0:44 offset1:46
	s_waitcnt lgkmcnt(4)
	v_add_f32_e32 v138, v138, v139
	v_add_f32_e32 v0, v0, v138
	s_waitcnt lgkmcnt(3)
	v_mfma_f32_32x32x16_bf16 v[4:19], v[52:55], v[140:143], v[4:19]
	s_waitcnt lgkmcnt(2)
	v_mfma_f32_32x32x16_bf16 v[20:35], v[56:59], v[140:143], v[20:35]
	s_waitcnt lgkmcnt(1)
	v_mfma_f32_32x32x16_bf16 v[4:19], v[60:63], v[144:147], v[4:19]
	s_waitcnt lgkmcnt(0)
	v_mfma_f32_32x32x16_bf16 v[20:35], v[64:67], v[144:147], v[20:35]
	s_xor_b32 s9, s9, 64
	v_add_u32_e32 v36, s9, v131
	s_movk_i32 s13, 0xd0
	v_mad_u64_u32 v[36:37], s[10:11], v36, s13, v[112:113]
	s_waitcnt vmcnt(4)
	ds_write_b128 v36, v[108:111]
	v_add_u32_e32 v36, s9, v132
	v_mad_u64_u32 v[36:37], s[10:11], v36, s13, v[114:115]
	s_waitcnt vmcnt(3)
	ds_write_b128 v36, v[104:107]
	v_add_u32_e32 v36, s9, v133
	v_mad_u64_u32 v[36:37], s[10:11], v36, s13, v[116:117]
	s_waitcnt vmcnt(2)
	ds_write_b128 v36, v[100:103]
	v_add_u32_e32 v36, s9, v129
	v_mul_lo_u32 v36, v36, s12
	s_movk_i32 s10, 0x6800
	v_add3_u32 v36, v134, v36, s10
	s_waitcnt vmcnt(1)
	ds_write2_b64 v36, v[96:97], v[98:99] offset1:1
	v_add_u32_e32 v36, s9, v130
	v_mul_lo_u32 v36, v36, s12
	v_add3_u32 v36, v134, v36, s10
	s_mov_b64 s[10:11], 0x80
	s_add_i32 s8, s8, 64
	v_lshl_add_u64 v[118:119], v[118:119], 0, s[10:11]
	v_lshl_add_u64 v[120:121], v[120:121], 0, s[10:11]
	s_mov_b64 s[10:11], 0x3000
	s_movk_i32 s37, 0xd0
	s_movk_i32 s71, 0x88
	v_lshl_add_u64 v[122:123], v[122:123], 0, s[10:11]
	v_lshl_add_u64 v[124:125], v[124:125], 0, s[10:11]
	s_cmpk_eq_i32 s8, 0x10c0
	s_mov_b64 s[68:69], 0x3000
	v_lshl_add_u64 v[126:127], v[126:127], 0, s[10:11]
	s_waitcnt vmcnt(0)
	ds_write2_b64 v36, v[92:93], v[94:95] offset1:1
	s_waitcnt lgkmcnt(0)
	s_barrier
	s_cbranch_scc1 .LBB0_419
	v_mov_b32_e32 v136, v137
	s_branch .LBB0_414

; DI bf16_t f2bf(float x) { unsigned r; asm("v_cvt_pk_bf16_f32 %0, %1, %1" : "=v"(r) : "v"(x)); return (bf16_t)r; }
; DI int crow(int reg, int h) { return (reg & 3) + 8 * (reg >> 2) + 4 * h; }
; #define XCD_TILE_LOOP(MT, NTN, m_, n_) for (int lt_ = (bid >> 3), m_ = 0, n_ = 0; (lt_ < ((MT) >> 3) * (NTN)) && ((m_ = (bid & 7) + 8 * (lt_ / (NTN))), (n_ = lt_ % (NTN)), true); lt_ += (G >> 3))
; template <class Epi, class ColV>
; DI void gemm_tile(const bf16_t* __restrict__ A, int lda, const bf16_t* __restrict__ Bt, int ldb, int K, int m0, int n0, unsigned char* smem, Epi epi, ColV colv, const bf16_t* __restrict__ HYT = nullptr) {
;     ...
;     const float cv0 = colv(m0, n0 + 64 * wc + li), cv1 = colv(m0, n0 + 64 * wc + 32 + li);
; #pragma unroll
;     for (int mi = 0; mi < 2; ++mi)
; #pragma unroll
;         for (int ni = 0; ni < 2; ++ni)
; #pragma unroll
;             for (int reg = 0; reg < 16; ++reg)
;                 epi(m0 + 64 * wr + 32 * mi + crow(reg, lh), n0 + 64 * wc + 32 * ni + li, acc[mi][ni][reg], ni ? cv1 : cv0);
;     ...
;         auto epi = [&](int r, int c, float v, float) { PROJ[(size_t)r * INP + c] = f2bf(v); };
;         auto nocol = [&](int, int) { return 0.f; };
;         XCD_TILE_LOOP(NT / 128, INP / 128, tm, tn) gemm_tile((const bf16_t*)(p.ws + WS_H), 1024, (const bf16_t*)(p.ws + wbase(layer) + W_IN), 1024, 1024, tm * 128, tn * 128, smem, epi, nocol);
.LBB0_1555:
	v_add_u32_e32 v0, s18, v193
	v_lshl_or_b32 v0, v166, 2, v0
	v_or3_b32 v1, v151, s15, v148
	v_mul_u32_u24_e32 v0, 0x1200, v0
	v_lshl_add_u32 v0, v1, 1, v0
	v_cvt_pk_bf16_f32 v1, v52, v52
	v_cvt_pk_bf16_f32 v2, v36, v36
	global_store_short v0, v1, s[2:3]
	global_store_short v0, v2, s[2:3] offset:64
	v_add_u32_e32 v0, 0x1200, v0
	v_cvt_pk_bf16_f32 v70, v53, v53
	v_cvt_pk_bf16_f32 v71, v37, v37
	global_store_short v0, v70, s[2:3]
	global_store_short v0, v71, s[2:3] offset:64
	v_add_u32_e32 v0, 0x1200, v0
	v_cvt_pk_bf16_f32 v1, v54, v54
	v_cvt_pk_bf16_f32 v2, v38, v38
	global_store_short v0, v1, s[2:3]
	global_store_short v0, v2, s[2:3] offset:64
	v_add_u32_e32 v0, 0x1200, v0
	v_cvt_pk_bf16_f32 v70, v55, v55
	v_cvt_pk_bf16_f32 v71, v39, v39
	global_store_short v0, v70, s[2:3]
	global_store_short v0, v71, s[2:3] offset:64
	v_add_u32_e32 v0, 0x5a00, v0
	v_cvt_pk_bf16_f32 v1, v56, v56
	v_cvt_pk_bf16_f32 v2, v40, v40
	global_store_short v0, v1, s[2:3]
	global_store_short v0, v2, s[2:3] offset:64
	v_add_u32_e32 v0, 0x1200, v0
	v_cvt_pk_bf16_f32 v70, v57, v57
	v_cvt_pk_bf16_f32 v71, v41, v41
	global_store_short v0, v70, s[2:3]
	global_store_short v0, v71, s[2:3] offset:64
	v_add_u32_e32 v0, 0x1200, v0
	v_cvt_pk_bf16_f32 v1, v58, v58
	v_cvt_pk_bf16_f32 v2, v42, v42
	global_store_short v0, v1, s[2:3]
	global_store_short v0, v2, s[2:3] offset:64
	v_add_u32_e32 v0, 0x1200, v0
	v_cvt_pk_bf16_f32 v70, v59, v59
	v_cvt_pk_bf16_f32 v71, v43, v43
	global_store_short v0, v70, s[2:3]
	global_store_short v0, v71, s[2:3] offset:64
	v_add_u32_e32 v0, 0x5a00, v0
	v_cvt_pk_bf16_f32 v1, v60, v60
	v_cvt_pk_bf16_f32 v2, v44, v44
	global_store_short v0, v1, s[2:3]
	global_store_short v0, v2, s[2:3] offset:64
	v_add_u32_e32 v0, 0x1200, v0
	v_cvt_pk_bf16_f32 v70, v61, v61
	v_cvt_pk_bf16_f32 v71, v45, v45
	global_store_short v0, v70, s[2:3]
	global_store_short v0, v71, s[2:3] offset:64
	v_add_u32_e32 v0, 0x1200, v0
	v_cvt_pk_bf16_f32 v1, v62, v62
	v_cvt_pk_bf16_f32 v2, v46, v46
	global_store_short v0, v1, s[2:3]
	global_store_short v0, v2, s[2:3] offset:64
	v_add_u32_e32 v0, 0x1200, v0
	v_cvt_pk_bf16_f32 v70, v63, v63
	v_cvt_pk_bf16_f32 v71, v47, v47
	global_store_short v0, v70, s[2:3]
	global_store_short v0, v71, s[2:3] offset:64
	v_add_u32_e32 v0, 0x5a00, v0
	v_cvt_pk_bf16_f32 v1, v64, v64
	v_cvt_pk_bf16_f32 v2, v48, v48
	global_store_short v0, v1, s[2:3]
	global_store_short v0, v2, s[2:3] offset:64
	v_add_u32_e32 v0, 0x1200, v0
	v_cvt_pk_bf16_f32 v70, v65, v65
	v_cvt_pk_bf16_f32 v71, v49, v49
	global_store_short v0, v70, s[2:3]
	global_store_short v0, v71, s[2:3] offset:64
	v_add_u32_e32 v0, 0x1200, v0
	v_cvt_pk_bf16_f32 v1, v66, v66
	v_cvt_pk_bf16_f32 v2, v50, v50
	global_store_short v0, v1, s[2:3]
	global_store_short v0, v2, s[2:3] offset:64
	v_add_u32_e32 v0, 0x1200, v0
	v_cvt_pk_bf16_f32 v70, v67, v67
	v_cvt_pk_bf16_f32 v71, v51, v51
	global_store_short v0, v70, s[2:3]
	global_store_short v0, v71, s[2:3] offset:64
	v_add_u32_e32 v0, 0x5a00, v0
	v_cvt_pk_bf16_f32 v1, v20, v20
	v_cvt_pk_bf16_f32 v2, v4, v4
	global_store_short v0, v1, s[2:3]
	global_store_short v0, v2, s[2:3] offset:64
	v_add_u32_e32 v0, 0x1200, v0
	v_cvt_pk_bf16_f32 v70, v21, v21
	v_cvt_pk_bf16_f32 v71, v5, v5
	global_store_short v0, v70, s[2:3]
	global_store_short v0, v71, s[2:3] offset:64
	v_add_u32_e32 v0, 0x1200, v0
	v_cvt_pk_bf16_f32 v1, v22, v22
	v_cvt_pk_bf16_f32 v2, v6, v6
	global_store_short v0, v1, s[2:3]
	global_store_short v0, v2, s[2:3] offset:64
	v_add_u32_e32 v0, 0x1200, v0
	v_cvt_pk_bf16_f32 v70, v23, v23
	v_cvt_pk_bf16_f32 v71, v7, v7
	global_store_short v0, v70, s[2:3]
	global_store_short v0, v71, s[2:3] offset:64
	v_add_u32_e32 v0, 0x5a00, v0
	v_cvt_pk_bf16_f32 v1, v24, v24
	v_cvt_pk_bf16_f32 v2, v8, v8
	global_store_short v0, v1, s[2:3]
	global_store_short v0, v2, s[2:3] offset:64
	v_add_u32_e32 v0, 0x1200, v0
	v_cvt_pk_bf16_f32 v70, v25, v25
	v_cvt_pk_bf16_f32 v71, v9, v9
	global_store_short v0, v70, s[2:3]
	global_store_short v0, v71, s[2:3] offset:64
	v_add_u32_e32 v0, 0x1200, v0
	v_cvt_pk_bf16_f32 v1, v26, v26
	v_cvt_pk_bf16_f32 v2, v10, v10
	global_store_short v0, v1, s[2:3]
	global_store_short v0, v2, s[2:3] offset:64
	v_add_u32_e32 v0, 0x1200, v0
	v_cvt_pk_bf16_f32 v70, v27, v27
	v_cvt_pk_bf16_f32 v71, v11, v11
	global_store_short v0, v70, s[2:3]
	global_store_short v0, v71, s[2:3] offset:64
	v_add_u32_e32 v0, 0x5a00, v0
	v_cvt_pk_bf16_f32 v1, v28, v28
	v_cvt_pk_bf16_f32 v2, v12, v12
	global_store_short v0, v1, s[2:3]
	global_store_short v0, v2, s[2:3] offset:64
	v_add_u32_e32 v0, 0x1200, v0
	v_cvt_pk_bf16_f32 v70, v29, v29
	v_cvt_pk_bf16_f32 v71, v13, v13
	global_store_short v0, v70, s[2:3]
	global_store_short v0, v71, s[2:3] offset:64
	v_add_u32_e32 v0, 0x1200, v0
	v_cvt_pk_bf16_f32 v1, v30, v30
	v_cvt_pk_bf16_f32 v2, v14, v14
	global_store_short v0, v1, s[2:3]
	global_store_short v0, v2, s[2:3] offset:64
	v_add_u32_e32 v0, 0x1200, v0
	v_cvt_pk_bf16_f32 v70, v31, v31
	v_cvt_pk_bf16_f32 v71, v15, v15
	global_store_short v0, v70, s[2:3]
	global_store_short v0, v71, s[2:3] offset:64
	v_add_u32_e32 v0, 0x5a00, v0
	v_cvt_pk_bf16_f32 v1, v32, v32
	v_cvt_pk_bf16_f32 v2, v16, v16
	global_store_short v0, v1, s[2:3]
	global_store_short v0, v2, s[2:3] offset:64
	v_add_u32_e32 v0, 0x1200, v0
	v_cvt_pk_bf16_f32 v70, v33, v33
	v_cvt_pk_bf16_f32 v71, v17, v17
	global_store_short v0, v70, s[2:3]
	global_store_short v0, v71, s[2:3] offset:64
	v_add_u32_e32 v0, 0x1200, v0
	v_cvt_pk_bf16_f32 v1, v34, v34
	v_cvt_pk_bf16_f32 v2, v18, v18
	global_store_short v0, v1, s[2:3]
	global_store_short v0, v2, s[2:3] offset:64
	v_add_u32_e32 v0, 0x1200, v0
	v_cvt_pk_bf16_f32 v70, v35, v35
	v_cvt_pk_bf16_f32 v71, v19, v19
	global_store_short v0, v70, s[2:3]
	global_store_short v0, v71, s[2:3] offset:64
	s_add_i32 s14, s14, s9
	s_cmpk_lt_i32 s14, 0x132
	s_cbranch_scc0 .LBB0_1564
